# gate/up K-loop: LDS-DMA loads use scalar-base + 32-bit offset form, no per-load 64-bit VALU adds
# baseline (speedup 1.0000x reference)
; #define PG8_STAGE(bufoff, gbase, voff) do { _Pragma("unroll") for (int _i = 0; _i < 2; ++_i) \
;         __builtin_amdgcn_global_load_lds((const unsigned*)((const char*)(gbase) + (voff)[_i]), (LAS unsigned*)(lds + (bufoff) + ldsw + _i * 8192), 16, 0, 0); } while (0)
; #define PG8_LDA(dst, b, h) do { _Pragma("unroll") for (int m = 0; m < 4; ++m) _Pragma("unroll") for (int k = 0; k < 2; ++k) dst[m][k] = *(const LAS bf16x8*)(pA + PG8_SA(b, h) + m * 2048 + k * 1024); } while (0)
; #define PG8_LDB(dst, b, h) do { _Pragma("unroll") for (int n = 0; n < 2; ++n) _Pragma("unroll") for (int k = 0; k < 2; ++k) dst[n][k] = *(const LAS bf16x8*)(pB + (PG8_SB(b, h) - 4 * HTB) + n * 2048 + k * 1024); } while (0)
; #define PG8_MMA(ai, bj, At, Bt) do { __builtin_amdgcn_s_setprio(1); _Pragma("unroll") for (int m = 0; m < 4; ++m) _Pragma("unroll") for (int n = 0; n < 2; ++n) _Pragma("unroll") for (int k = 0; k < 2; ++k) \
;         acc[ai][bj][m][n] = __builtin_amdgcn_mfma_f32_16x16x32_bf16(Bt[n][k], At[m][k], acc[ai][bj][m][n], 0, 0, 0); __builtin_amdgcn_s_setprio(0); } while (0)
; #define PG8_WAIT_V(n) asm volatile("s_waitcnt vmcnt(" #n ")" ::: "memory")
; #define PG8_WAIT_L(n) asm volatile("s_waitcnt lgkmcnt(" #n ")" ::: "memory")
; #define PG8_BAR __builtin_amdgcn_s_barrier()
; #define PG8_SCHED __builtin_amdgcn_sched_barrier(0)
; template <class Desc, class Epi, bool ALIGN_EPI>
; __device__ __forceinline__ void gemm_phase(LAS unsigned char* lds, const Desc& D, const Epi& E, int G, int c) {
;     ...
;             const char* a1 = cA + (size_t)(t + 1) * kstep;
;             const char* a2 = last ? nA : cA + (size_t)(t + 2) * kstep; const char* b2 = last ? nB : cB + (size_t)(t + 2) * kstep;
;             const char* a3 = a2 + kstep; const char* b3 = b2 + kstep;
;             PG8_LDB(B0, 0, 0); PG8_LDB(B1, 0, 1); PG8_SCHED; PG8_LDA(At, 0, 0); PG8_STAGE(PG8_SA(1, 1), a1 + hstepA, voffA);
;             PG8_WAIT_V(8); PG8_WAIT_L(0); PG8_BAR; PG8_MMA(0, 0, At, B0); PG8_MMA(0, 1, At, B1); PG8_BAR; PG8_SCHED;
;             PG8_LDA(At, 0, 1); PG8_STAGE(PG8_SB(0, 0), b2, voffB); PG8_STAGE(PG8_SB(0, 1), b2 + hstepB, voffB); PG8_STAGE(PG8_SA(0, 0), a2, voffA);
;             PG8_WAIT_V(8); PG8_WAIT_L(0); PG8_BAR; PG8_MMA(1, 0, At, B0); PG8_MMA(1, 1, At, B1); PG8_BAR; PG8_SCHED;
.LBB0_1580:
	s_or_b32 s14, s30, 1
	s_add_i32 s30, s30, 2
	s_mov_b32 s31, s15
	s_lshl_b64 s[72:73], s[14:15], 7
	s_lshl_b64 s[74:75], s[30:31], 7
	s_add_u32 s14, s18, s74
	ds_read_b128 v[140:143], v163
	ds_read_b128 v[144:147], v163 offset:1024
	ds_read_b128 v[148:151], v163 offset:2048
	ds_read_b128 v[152:155], v163 offset:3072
	ds_read_b128 v[156:159], v163 offset:16384
	ds_read_b128 v[166:169], v163 offset:17408
	ds_read_b128 v[170:173], v163 offset:18432
	ds_read_b128 v[174:177], v163 offset:19456
	s_addc_u32 s31, s19, s75
	s_and_b64 s[46:47], s[34:35], exec
	s_cselect_b32 s47, s43, s31
	s_cselect_b32 s46, s42, s14
	s_add_u32 s14, s20, s74
	s_addc_u32 s31, s21, s75
	s_and_b64 s[34:35], s[34:35], exec
	s_cselect_b32 s35, s3, s31
	s_cselect_b32 s34, s13, s14
	s_add_u32 s14, s18, s72
	s_addc_u32 s31, s19, s73
	s_add_u32 s72, s14, 0x100000
	s_addc_u32 s73, s31, 0
	s_add_i32 m0, s52, 0xc000
	ds_read_b128 v[178:181], v162
	ds_read_b128 v[182:185], v162 offset:1024
	ds_read_b128 v[186:189], v162 offset:2048
	ds_read_b128 v[190:193], v162 offset:3072
	ds_read_b128 v[194:197], v162 offset:4096
	ds_read_b128 v[198:201], v162 offset:5120
	ds_read_b128 v[202:205], v162 offset:6144
	ds_read_b128 v[206:209], v162 offset:7168
	global_load_lds_dwordx4 v132, s[72:73]
	s_add_i32 m0, s52, 0xe000
	s_nop 0
	global_load_lds_dwordx4 v136, s[72:73]
	s_waitcnt vmcnt(8)
	s_waitcnt lgkmcnt(0)
	s_barrier
	s_setprio 1
	s_waitcnt lgkmcnt(0)
	v_mfma_f32_16x16x32_bf16 v[128:131], v[140:143], v[178:181], v[128:131]
	v_mfma_f32_16x16x32_bf16 v[124:127], v[148:151], v[178:181], v[124:127]
	v_mfma_f32_16x16x32_bf16 v[120:123], v[140:143], v[186:189], v[120:123]
	v_mfma_f32_16x16x32_bf16 v[116:119], v[148:151], v[186:189], v[116:119]
	v_mfma_f32_16x16x32_bf16 v[112:115], v[140:143], v[194:197], v[112:115]
	v_mfma_f32_16x16x32_bf16 v[108:111], v[148:151], v[194:197], v[108:111]
	v_mfma_f32_16x16x32_bf16 v[104:107], v[140:143], v[202:205], v[104:107]
	v_mfma_f32_16x16x32_bf16 v[100:103], v[148:151], v[202:205], v[100:103]
	v_mfma_f32_16x16x32_bf16 v[128:131], v[144:147], v[182:185], v[128:131]
	v_mfma_f32_16x16x32_bf16 v[124:127], v[152:155], v[182:185], v[124:127]
	v_mfma_f32_16x16x32_bf16 v[120:123], v[144:147], v[190:193], v[120:123]
	v_mfma_f32_16x16x32_bf16 v[116:119], v[152:155], v[190:193], v[116:119]
	v_mfma_f32_16x16x32_bf16 v[112:115], v[144:147], v[198:201], v[112:115]
	v_mfma_f32_16x16x32_bf16 v[108:111], v[152:155], v[198:201], v[108:111]
	v_mfma_f32_16x16x32_bf16 v[104:107], v[144:147], v[206:209], v[104:107]
	v_mfma_f32_16x16x32_bf16 v[100:103], v[152:155], v[206:209], v[100:103]
	s_setprio 0
	s_setprio 1
	v_mfma_f32_16x16x32_bf16 v[96:99], v[156:159], v[178:181], v[96:99]
	v_mfma_f32_16x16x32_bf16 v[92:95], v[170:173], v[178:181], v[92:95]
	v_mfma_f32_16x16x32_bf16 v[88:91], v[156:159], v[186:189], v[88:91]
	v_mfma_f32_16x16x32_bf16 v[84:87], v[170:173], v[186:189], v[84:87]
	v_mfma_f32_16x16x32_bf16 v[80:83], v[156:159], v[194:197], v[80:83]
	v_mfma_f32_16x16x32_bf16 v[76:79], v[170:173], v[194:197], v[76:79]
	v_mfma_f32_16x16x32_bf16 v[72:75], v[156:159], v[202:205], v[72:75]
	v_mfma_f32_16x16x32_bf16 v[68:71], v[170:173], v[202:205], v[68:71]
	v_mfma_f32_16x16x32_bf16 v[96:99], v[166:169], v[182:185], v[96:99]
	v_mfma_f32_16x16x32_bf16 v[92:95], v[174:177], v[182:185], v[92:95]
	v_mfma_f32_16x16x32_bf16 v[88:91], v[166:169], v[190:193], v[88:91]
	v_mfma_f32_16x16x32_bf16 v[84:87], v[174:177], v[190:193], v[84:87]
	v_mfma_f32_16x16x32_bf16 v[80:83], v[166:169], v[198:201], v[80:83]
	v_mfma_f32_16x16x32_bf16 v[76:79], v[174:177], v[198:201], v[76:79]
	v_mfma_f32_16x16x32_bf16 v[72:75], v[166:169], v[206:209], v[72:75]
	v_mfma_f32_16x16x32_bf16 v[68:71], v[174:177], v[206:209], v[68:71]
	s_setprio 0
	s_barrier
	s_mov_b32 m0, s53
	s_add_u32 s72, s34, 0x100000
	s_addc_u32 s73, s35, 0
	ds_read_b128 v[178:181], v162 offset:16384
	ds_read_b128 v[182:185], v162 offset:17408
	ds_read_b128 v[186:189], v162 offset:18432
	ds_read_b128 v[190:193], v162 offset:19456
	ds_read_b128 v[194:197], v162 offset:20480
	ds_read_b128 v[198:201], v162 offset:21504
	ds_read_b128 v[202:205], v162 offset:22528
	ds_read_b128 v[206:209], v162 offset:23552
	global_load_lds_dwordx4 v134, s[34:35]
	s_mov_b32 m0, s54
	s_nop 0
	global_load_lds_dwordx4 v138, s[34:35]
	s_mov_b32 m0, s55
	s_nop 0
	global_load_lds_dwordx4 v134, s[72:73]
	s_mov_b32 m0, s56
	s_nop 0
	global_load_lds_dwordx4 v138, s[72:73]
	s_mov_b32 m0, s52
	s_nop 0
	global_load_lds_dwordx4 v132, s[46:47]
	s_mov_b32 m0, s57
	s_nop 0
	global_load_lds_dwordx4 v136, s[46:47]
	s_waitcnt vmcnt(8)
	s_waitcnt lgkmcnt(0)
	s_barrier
; #define PG8_STAGE(bufoff, gbase, voff) do { _Pragma("unroll") for (int _i = 0; _i < 2; ++_i) \
;         __builtin_amdgcn_global_load_lds((const unsigned*)((const char*)(gbase) + (voff)[_i]), (LAS unsigned*)(lds + (bufoff) + ldsw + _i * 8192), 16, 0, 0); } while (0)
; #define PG8_LDA(dst, b, h) do { _Pragma("unroll") for (int m = 0; m < 4; ++m) _Pragma("unroll") for (int k = 0; k < 2; ++k) dst[m][k] = *(const LAS bf16x8*)(pA + PG8_SA(b, h) + m * 2048 + k * 1024); } while (0)
; #define PG8_LDB(dst, b, h) do { _Pragma("unroll") for (int n = 0; n < 2; ++n) _Pragma("unroll") for (int k = 0; k < 2; ++k) dst[n][k] = *(const LAS bf16x8*)(pB + (PG8_SB(b, h) - 4 * HTB) + n * 2048 + k * 1024); } while (0)
; #define PG8_MMA(ai, bj, At, Bt) do { __builtin_amdgcn_s_setprio(1); _Pragma("unroll") for (int m = 0; m < 4; ++m) _Pragma("unroll") for (int n = 0; n < 2; ++n) _Pragma("unroll") for (int k = 0; k < 2; ++k) \
;         acc[ai][bj][m][n] = __builtin_amdgcn_mfma_f32_16x16x32_bf16(Bt[n][k], At[m][k], acc[ai][bj][m][n], 0, 0, 0); __builtin_amdgcn_s_setprio(0); } while (0)
; #define PG8_WAIT_V(n) asm volatile("s_waitcnt vmcnt(" #n ")" ::: "memory")
; #define PG8_WAIT_L(n) asm volatile("s_waitcnt lgkmcnt(" #n ")" ::: "memory")
; #define PG8_BAR __builtin_amdgcn_s_barrier()
; #define PG8_SCHED __builtin_amdgcn_sched_barrier(0)
; template <class Desc, class Epi, bool ALIGN_EPI>
; __device__ __forceinline__ void gemm_phase(LAS unsigned char* lds, const Desc& D, const Epi& E, int G, int c) {
;     ...
;             PG8_WAIT_V(8); PG8_WAIT_L(0); PG8_BAR; PG8_MMA(1, 0, At, B0); PG8_MMA(1, 1, At, B1); PG8_BAR; PG8_SCHED;
;             PG8_LDB(B0, 1, 0); PG8_LDB(B1, 1, 1); PG8_SCHED; PG8_LDA(At, 1, 0); PG8_STAGE(PG8_SA(0, 1), a2 + hstepA, voffA);
;             PG8_WAIT_V(8); PG8_WAIT_L(0); PG8_BAR; PG8_MMA(0, 0, At, B0); PG8_MMA(0, 1, At, B1); PG8_BAR; PG8_SCHED;
	s_setprio 1
	s_waitcnt lgkmcnt(0)
	v_mfma_f32_16x16x32_bf16 v[64:67], v[140:143], v[178:181], v[64:67]
	v_mfma_f32_16x16x32_bf16 v[52:55], v[148:151], v[178:181], v[52:55]
	v_mfma_f32_16x16x32_bf16 v[32:35], v[140:143], v[186:189], v[32:35]
	v_mfma_f32_16x16x32_bf16 v[20:23], v[148:151], v[186:189], v[20:23]
	v_mfma_f32_16x16x32_bf16 v[16:19], v[140:143], v[194:197], v[16:19]
	v_mfma_f32_16x16x32_bf16 v[12:15], v[148:151], v[194:197], v[12:15]
	v_mfma_f32_16x16x32_bf16 v[8:11], v[140:143], v[202:205], v[8:11]
	v_mfma_f32_16x16x32_bf16 v[4:7], v[148:151], v[202:205], v[4:7]
	v_mfma_f32_16x16x32_bf16 v[64:67], v[144:147], v[182:185], v[64:67]
	v_mfma_f32_16x16x32_bf16 v[52:55], v[152:155], v[182:185], v[52:55]
	v_mfma_f32_16x16x32_bf16 v[32:35], v[144:147], v[190:193], v[32:35]
	v_mfma_f32_16x16x32_bf16 v[20:23], v[152:155], v[190:193], v[20:23]
	v_mfma_f32_16x16x32_bf16 v[16:19], v[144:147], v[198:201], v[16:19]
	v_mfma_f32_16x16x32_bf16 v[12:15], v[152:155], v[198:201], v[12:15]
	v_mfma_f32_16x16x32_bf16 v[8:11], v[144:147], v[206:209], v[8:11]
	v_mfma_f32_16x16x32_bf16 v[4:7], v[152:155], v[206:209], v[4:7]
	s_setprio 0
	s_setprio 1
	v_mfma_f32_16x16x32_bf16 v[60:63], v[156:159], v[178:181], v[60:63]
	v_mfma_f32_16x16x32_bf16 v[56:59], v[170:173], v[178:181], v[56:59]
	v_mfma_f32_16x16x32_bf16 v[48:51], v[156:159], v[186:189], v[48:51]
	v_mfma_f32_16x16x32_bf16 v[44:47], v[170:173], v[186:189], v[44:47]
	v_mfma_f32_16x16x32_bf16 v[40:43], v[156:159], v[194:197], v[40:43]
	v_mfma_f32_16x16x32_bf16 v[36:39], v[170:173], v[194:197], v[36:39]
	v_mfma_f32_16x16x32_bf16 v[28:31], v[156:159], v[202:205], v[28:31]
	v_mfma_f32_16x16x32_bf16 v[24:27], v[170:173], v[202:205], v[24:27]
	v_mfma_f32_16x16x32_bf16 v[60:63], v[166:169], v[182:185], v[60:63]
	v_mfma_f32_16x16x32_bf16 v[56:59], v[174:177], v[182:185], v[56:59]
	v_mfma_f32_16x16x32_bf16 v[48:51], v[166:169], v[190:193], v[48:51]
	v_mfma_f32_16x16x32_bf16 v[44:47], v[174:177], v[190:193], v[44:47]
	v_mfma_f32_16x16x32_bf16 v[40:43], v[166:169], v[198:201], v[40:43]
	v_mfma_f32_16x16x32_bf16 v[36:39], v[174:177], v[198:201], v[36:39]
	v_mfma_f32_16x16x32_bf16 v[28:31], v[166:169], v[206:209], v[28:31]
	v_mfma_f32_16x16x32_bf16 v[24:27], v[174:177], v[206:209], v[24:27]
	s_setprio 0
	s_barrier
	ds_read_b128 v[140:143], v163 offset:32768
	ds_read_b128 v[144:147], v163 offset:33792
	ds_read_b128 v[148:151], v163 offset:34816
	ds_read_b128 v[152:155], v163 offset:35840
	ds_read_b128 v[156:159], v163 offset:49152
	ds_read_b128 v[166:169], v163 offset:50176
	ds_read_b128 v[170:173], v163 offset:51200
	ds_read_b128 v[174:177], v163 offset:52224
	s_add_u32 s46, s46, 0x100000
	s_addc_u32 s47, s47, 0
	s_mov_b32 m0, s58
	ds_read_b128 v[178:181], v162 offset:32768
	ds_read_b128 v[182:185], v162 offset:33792
	ds_read_b128 v[186:189], v162 offset:34816
	ds_read_b128 v[190:193], v162 offset:35840
	ds_read_b128 v[194:197], v162 offset:36864
	ds_read_b128 v[198:201], v162 offset:37888
	ds_read_b128 v[202:205], v162 offset:38912
	ds_read_b128 v[206:209], v162 offset:39936
	global_load_lds_dwordx4 v132, s[46:47]
	s_mov_b32 m0, s59
	s_nop 0
	global_load_lds_dwordx4 v136, s[46:47]
	s_waitcnt vmcnt(8)
	s_waitcnt lgkmcnt(0)
	s_barrier
	s_setprio 1
	s_waitcnt lgkmcnt(0)
	v_mfma_f32_16x16x32_bf16 v[128:131], v[140:143], v[178:181], v[128:131]
	v_mfma_f32_16x16x32_bf16 v[124:127], v[148:151], v[178:181], v[124:127]
	v_mfma_f32_16x16x32_bf16 v[120:123], v[140:143], v[186:189], v[120:123]
	v_mfma_f32_16x16x32_bf16 v[116:119], v[148:151], v[186:189], v[116:119]
	v_mfma_f32_16x16x32_bf16 v[112:115], v[140:143], v[194:197], v[112:115]
	v_mfma_f32_16x16x32_bf16 v[108:111], v[148:151], v[194:197], v[108:111]
	v_mfma_f32_16x16x32_bf16 v[104:107], v[140:143], v[202:205], v[104:107]
	v_mfma_f32_16x16x32_bf16 v[100:103], v[148:151], v[202:205], v[100:103]
	v_mfma_f32_16x16x32_bf16 v[128:131], v[144:147], v[182:185], v[128:131]
	v_mfma_f32_16x16x32_bf16 v[124:127], v[152:155], v[182:185], v[124:127]
	v_mfma_f32_16x16x32_bf16 v[120:123], v[144:147], v[190:193], v[120:123]
	v_mfma_f32_16x16x32_bf16 v[116:119], v[152:155], v[190:193], v[116:119]
	v_mfma_f32_16x16x32_bf16 v[112:115], v[144:147], v[198:201], v[112:115]
	v_mfma_f32_16x16x32_bf16 v[108:111], v[152:155], v[198:201], v[108:111]
	v_mfma_f32_16x16x32_bf16 v[104:107], v[144:147], v[206:209], v[104:107]
	v_mfma_f32_16x16x32_bf16 v[100:103], v[152:155], v[206:209], v[100:103]
	s_setprio 0
	s_setprio 1
	v_mfma_f32_16x16x32_bf16 v[96:99], v[156:159], v[178:181], v[96:99]
	v_mfma_f32_16x16x32_bf16 v[92:95], v[170:173], v[178:181], v[92:95]
	v_mfma_f32_16x16x32_bf16 v[88:91], v[156:159], v[186:189], v[88:91]
	v_mfma_f32_16x16x32_bf16 v[84:87], v[170:173], v[186:189], v[84:87]
	v_mfma_f32_16x16x32_bf16 v[80:83], v[156:159], v[194:197], v[80:83]
	v_mfma_f32_16x16x32_bf16 v[76:79], v[170:173], v[194:197], v[76:79]
	v_mfma_f32_16x16x32_bf16 v[72:75], v[156:159], v[202:205], v[72:75]
	v_mfma_f32_16x16x32_bf16 v[68:71], v[170:173], v[202:205], v[68:71]
	v_mfma_f32_16x16x32_bf16 v[96:99], v[166:169], v[182:185], v[96:99]
	v_mfma_f32_16x16x32_bf16 v[92:95], v[174:177], v[182:185], v[92:95]
	v_mfma_f32_16x16x32_bf16 v[88:91], v[166:169], v[190:193], v[88:91]
	v_mfma_f32_16x16x32_bf16 v[84:87], v[174:177], v[190:193], v[84:87]
	v_mfma_f32_16x16x32_bf16 v[80:83], v[166:169], v[198:201], v[80:83]
	v_mfma_f32_16x16x32_bf16 v[76:79], v[174:177], v[198:201], v[76:79]
	v_mfma_f32_16x16x32_bf16 v[72:75], v[166:169], v[206:209], v[72:75]
	v_mfma_f32_16x16x32_bf16 v[68:71], v[174:177], v[206:209], v[68:71]
	s_setprio 0
	s_barrier
;     __device__ __forceinline__ int nt(const Unit& u) const { return (u.pn >> 1) < 2 ? 22 : 20; }
; #define PG8_STAGE(bufoff, gbase, voff) do { _Pragma("unroll") for (int _i = 0; _i < 2; ++_i) \
;         __builtin_amdgcn_global_load_lds((const unsigned*)((const char*)(gbase) + (voff)[_i]), (LAS unsigned*)(lds + (bufoff) + ldsw + _i * 8192), 16, 0, 0); } while (0)
; #define PG8_LDA(dst, b, h) do { _Pragma("unroll") for (int m = 0; m < 4; ++m) _Pragma("unroll") for (int k = 0; k < 2; ++k) dst[m][k] = *(const LAS bf16x8*)(pA + PG8_SA(b, h) + m * 2048 + k * 1024); } while (0)
; #define PG8_MMA(ai, bj, At, Bt) do { __builtin_amdgcn_s_setprio(1); _Pragma("unroll") for (int m = 0; m < 4; ++m) _Pragma("unroll") for (int n = 0; n < 2; ++n) _Pragma("unroll") for (int k = 0; k < 2; ++k) \
;         acc[ai][bj][m][n] = __builtin_amdgcn_mfma_f32_16x16x32_bf16(Bt[n][k], At[m][k], acc[ai][bj][m][n], 0, 0, 0); __builtin_amdgcn_s_setprio(0); } while (0)
; #define PG8_WAIT_V(n) asm volatile("s_waitcnt vmcnt(" #n ")" ::: "memory")
; #define PG8_WAIT_L(n) asm volatile("s_waitcnt lgkmcnt(" #n ")" ::: "memory")
; #define PG8_BAR __builtin_amdgcn_s_barrier()
; #define PG8_SCHED __builtin_amdgcn_sched_barrier(0)
; template <class Desc, class Epi, bool ALIGN_EPI>
; __device__ __forceinline__ void gemm_phase(LAS unsigned char* lds, const Desc& D, const Epi& E, int G, int c) {
;     ...
;         for (int t = 0; t < nt; t += 2) {
;     ...
;             PG8_LDA(At, 1, 1); PG8_STAGE(PG8_SB(1, 0), b3, voffB); PG8_STAGE(PG8_SB(1, 1), b3 + hstepB, voffB); PG8_STAGE(PG8_SA(1, 0), a3, voffA);
;             PG8_WAIT_V(8); PG8_WAIT_L(0); PG8_BAR; PG8_MMA(1, 0, At, B0); PG8_MMA(1, 1, At, B1); PG8_BAR; PG8_SCHED;
;         }
	s_mov_b32 m0, s61
	s_add_u32 s74, s34, 0x80
	s_addc_u32 s75, s35, 0
	s_add_u32 s34, s34, 0x100080
	s_addc_u32 s35, s35, 0
	ds_read_b128 v[178:181], v162 offset:49152
	ds_read_b128 v[182:185], v162 offset:50176
	ds_read_b128 v[186:189], v162 offset:51200
	ds_read_b128 v[190:193], v162 offset:52224
	ds_read_b128 v[194:197], v162 offset:53248
	ds_read_b128 v[198:201], v162 offset:54272
	ds_read_b128 v[202:205], v162 offset:55296
	ds_read_b128 v[206:209], v162 offset:56320
	global_load_lds_dwordx4 v134, s[74:75]
	s_mov_b32 m0, s62
	s_nop 0
	global_load_lds_dwordx4 v138, s[74:75]
	s_mov_b32 m0, s65
	s_nop 0
	global_load_lds_dwordx4 v134, s[34:35]
	s_mov_b32 m0, s67
	s_nop 0
	global_load_lds_dwordx4 v138, s[34:35]
	s_sub_u32 s74, s46, 0xfff80
	s_subb_u32 s75, s47, 0
	s_mov_b32 m0, s63
	s_nop 0
	global_load_lds_dwordx4 v132, s[74:75]
	s_mov_b32 m0, s64
	s_nop 0
	global_load_lds_dwordx4 v136, s[74:75]
	s_waitcnt vmcnt(8)
	s_waitcnt lgkmcnt(0)
	s_barrier
	s_setprio 1
	s_waitcnt lgkmcnt(0)
	v_mfma_f32_16x16x32_bf16 v[64:67], v[140:143], v[178:181], v[64:67]
	v_mfma_f32_16x16x32_bf16 v[52:55], v[148:151], v[178:181], v[52:55]
	v_mfma_f32_16x16x32_bf16 v[32:35], v[140:143], v[186:189], v[32:35]
	v_mfma_f32_16x16x32_bf16 v[20:23], v[148:151], v[186:189], v[20:23]
	v_mfma_f32_16x16x32_bf16 v[16:19], v[140:143], v[194:197], v[16:19]
	v_mfma_f32_16x16x32_bf16 v[12:15], v[148:151], v[194:197], v[12:15]
	v_mfma_f32_16x16x32_bf16 v[8:11], v[140:143], v[202:205], v[8:11]
	v_mfma_f32_16x16x32_bf16 v[4:7], v[148:151], v[202:205], v[4:7]
	v_mfma_f32_16x16x32_bf16 v[64:67], v[144:147], v[182:185], v[64:67]
	v_mfma_f32_16x16x32_bf16 v[52:55], v[152:155], v[182:185], v[52:55]
	v_mfma_f32_16x16x32_bf16 v[32:35], v[144:147], v[190:193], v[32:35]
	v_mfma_f32_16x16x32_bf16 v[20:23], v[152:155], v[190:193], v[20:23]
	v_mfma_f32_16x16x32_bf16 v[16:19], v[144:147], v[198:201], v[16:19]
	v_mfma_f32_16x16x32_bf16 v[12:15], v[152:155], v[198:201], v[12:15]
	v_mfma_f32_16x16x32_bf16 v[8:11], v[144:147], v[206:209], v[8:11]
	v_mfma_f32_16x16x32_bf16 v[4:7], v[152:155], v[206:209], v[4:7]
	s_setprio 0
	s_setprio 1
	v_mfma_f32_16x16x32_bf16 v[60:63], v[156:159], v[178:181], v[60:63]
	v_mfma_f32_16x16x32_bf16 v[56:59], v[170:173], v[178:181], v[56:59]
	v_mfma_f32_16x16x32_bf16 v[48:51], v[156:159], v[186:189], v[48:51]
	v_mfma_f32_16x16x32_bf16 v[44:47], v[170:173], v[186:189], v[44:47]
	v_mfma_f32_16x16x32_bf16 v[40:43], v[156:159], v[194:197], v[40:43]
	v_mfma_f32_16x16x32_bf16 v[36:39], v[170:173], v[194:197], v[36:39]
	v_mfma_f32_16x16x32_bf16 v[28:31], v[156:159], v[202:205], v[28:31]
	v_mfma_f32_16x16x32_bf16 v[24:27], v[170:173], v[202:205], v[24:27]
	v_mfma_f32_16x16x32_bf16 v[60:63], v[166:169], v[182:185], v[60:63]
	v_mfma_f32_16x16x32_bf16 v[56:59], v[174:177], v[182:185], v[56:59]
	v_mfma_f32_16x16x32_bf16 v[48:51], v[166:169], v[190:193], v[48:51]
	v_mfma_f32_16x16x32_bf16 v[44:47], v[174:177], v[190:193], v[44:47]
	v_mfma_f32_16x16x32_bf16 v[40:43], v[166:169], v[198:201], v[40:43]
	v_mfma_f32_16x16x32_bf16 v[36:39], v[174:177], v[198:201], v[36:39]
	v_mfma_f32_16x16x32_bf16 v[28:31], v[166:169], v[206:209], v[28:31]
	v_mfma_f32_16x16x32_bf16 v[24:27], v[174:177], v[206:209], v[24:27]
	s_setprio 0
	s_barrier
	s_cmp_ge_u32 s30, s2
	s_cbranch_scc1 .LBB0_1591
